# split-K tail on both out-projection GEMMs (K=1024) + continuous 23-deep pipelined partial reload in all four split-K reducers; GEMM loop heads at offset 28
# baseline (speedup 1.0000x reference)
.LBB0_541:
	s_or_b64 exec, exec, s[4:5]
	s_mov_b64 s[8:9], s[0:1]
	s_waitcnt lgkmcnt(0)
	v_mov_b32_e32 v0, v188
	s_barrier
	s_add_i32 s4, 0, 0x24ffc
	v_mov_b32_e32 v0, s4
	ds_read_b32 v0, v0
	s_movk_i32 s4, 0x13f
	v_mov_b32_e32 v8, v188
	s_waitcnt lgkmcnt(0)
	v_cmp_lt_i32_e32 vcc, s4, v0
	v_readfirstlane_b32 s27, v0
	v_readfirstlane_b32 s16, v8
	s_cbranch_vccnz .Lp5_754
	v_lshlrev_b32_e32 v0, 4, v8
	v_add_u32_e32 v1, 0x2000, v0
	v_ashrrev_i32_e32 v2, 31, v1
	v_lshrrev_b32_e32 v2, 22, v2
	v_add_u32_e32 v2, v1, v2
	v_ashrrev_i32_e32 v9, 10, v2
	v_mul_i32_i24_e32 v2, 0x400, v9
	v_sub_u32_e32 v1, v1, v2
	v_lshrrev_b32_e32 v2, 4, v1
	v_bitop3_b32 v1, v2, v1, 32 bitop3:0x6c
	v_ashrrev_i32_e32 v2, 31, v1
	v_lshrrev_b32_e32 v2, 26, v2
	v_add_u32_e32 v2, v1, v2
	v_lshlrev_b32_e32 v3, 3, v9
	v_ashrrev_i32_e32 v10, 6, v2
	v_and_b32_e32 v3, -16, v3
	v_add_u32_e32 v3, v10, v3
	s_load_dwordx4 s[4:7], s[8:9], 0xa8
	v_and_b32_e32 v4, 3, v10
	s_mov_b32 s8, 0x1fffe0
	v_lshrrev_b32_e32 v5, 2, v3
	v_lshlrev_b32_e32 v6, 1, v3
	v_and_b32_e32 v2, 0xc0, v2
	v_and_or_b32 v4, v3, s8, v4
	v_and_b32_e32 v5, 4, v5
	v_and_b32_e32 v6, 24, v6
	v_sub_u32_e32 v1, v1, v2
	v_mov_b32_e32 v2, 1
	v_or3_b32 v4, v4, v5, v6
	v_lshlrev_b32_e32 v5, 5, v9
	v_ashrrev_i16_sdwa v1, v2, sext(v1) dst_sel:DWORD dst_unused:UNUSED_PAD src0_sel:DWORD src1_sel:BYTE_0
	v_and_b32_e32 v5, 32, v5
	v_bfe_i32 v11, v1, 0, 16
	v_add_lshl_u32 v1, v5, v11, 1
	v_lshl_add_u32 v128, v4, 11, v1
	v_lshl_add_u32 v130, v3, 11, v1
	v_bfe_i32 v1, v8, 27, 1
	v_lshrrev_b32_e32 v1, 22, v1
	v_add_u32_e32 v1, v0, v1
	v_and_b32_e32 v1, 0xfffffc00, v1
	v_sub_u32_e32 v0, v0, v1
	v_lshrrev_b32_e32 v1, 4, v0
	v_ashrrev_i32_e32 v3, 31, v8
	v_bitop3_b32 v0, v1, v0, 32 bitop3:0x6c
	v_lshrrev_b32_e32 v3, 26, v3
	v_ashrrev_i32_e32 v1, 31, v0
	v_add_u32_e32 v3, v8, v3
	v_lshrrev_b32_e32 v1, 26, v1
	v_ashrrev_i32_e32 v13, 6, v3
	v_add_u32_e32 v1, v0, v1
	v_lshlrev_b32_e32 v3, 3, v13
	s_waitcnt lgkmcnt(0)
	s_add_u32 s56, s6, 0xfa00000
	v_ashrrev_i32_e32 v12, 6, v1
	v_and_b32_e32 v3, -16, v3
	s_addc_u32 s57, s7, 0
	v_add_u32_e32 v3, v12, v3
	v_and_b32_e32 v4, 3, v12
	s_ashr_i32 s59, s27, 31
	v_and_or_b32 v4, v3, s8, v4
	s_and_b32 s8, s27, 7
	s_lshr_b32 s9, s27, 3
	s_and_b32 s98, s9, 3
	s_lshr_b32 s9, s9, 2
	s_lshl_b32 s99, s8, 3
	s_add_i32 s99, s99, s9
	s_mul_i32 s8, s8, 10
	s_cmp_eq_u32 s98, 3
	s_cbranch_scc1 .Lsk5_q3a
	s_lshr_b32 s10, s9, 2
	s_add_i32 s8, s8, s10
	s_add_i32 s8, s8, 8
	s_and_b32 s9, s9, 3
	s_lshl_b32 s10, s98, 9
	s_movk_i32 s100, 0
	s_branch .Lsk5_q3b
.Lsk5_q3a:
	s_add_i32 s8, s8, s9
	s_mov_b32 s9, 3
	s_mov_b32 s10, 0
	s_movk_i32 s100, 12
.Lsk5_q3b:
	s_lshl_b32 s8, s8, 2
	s_or_b32 s8, s8, s9
	s_mov_b32 s101, s10
	s_ashr_i32 s5, s16, 6
	s_ashr_i32 s4, s16, 8
	s_lshl_b32 s58, s5, 10
	v_lshrrev_b32_e32 v5, 2, v3
	v_lshlrev_b32_e32 v6, 1, v3
	v_and_b32_e32 v1, 0xc0, v1
	s_ashr_i32 s44, s8, 2
	v_and_b32_e32 v5, 4, v5
	v_and_b32_e32 v6, 24, v6
	v_sub_u32_e32 v0, v0, v1
	s_and_b32 s77, s8, 3
	s_ashr_i32 s45, s44, 31
	v_or3_b32 v4, v4, v5, v6
	v_lshlrev_b32_e32 v5, 5, v13
	v_ashrrev_i16_sdwa v0, v2, sext(v0) dst_sel:DWORD dst_unused:UNUSED_PAD src0_sel:DWORD src1_sel:BYTE_0
	s_lshl_b64 s[8:9], s[44:45], 19
	s_lshl_b32 s10, s77, 19
	s_add_u32 s10, s10, s101
	v_and_b32_e32 v5, 32, v5
	v_bfe_i32 v14, v0, 0, 16
	s_add_u32 s52, s56, s10
	v_add_lshl_u32 v0, v5, v14, 1
	s_addc_u32 s53, s57, 0
	s_add_i32 s45, s58, 0
	v_lshl_add_u32 v132, v4, 11, v0
	s_add_i32 m0, s45, 0x10000
	v_lshl_add_u32 v134, v3, 11, v0
	global_load_lds_dwordx4 v132, s[52:53]
	s_add_i32 m0, s45, 0x12000
	s_add_u32 s10, s52, 0x40000
	global_load_lds_dwordx4 v128, s[52:53]
	s_addc_u32 s11, s53, 0
	s_add_i32 m0, s45, 0x14000
	v_mov_b32_e32 v133, 0
	global_load_lds_dwordx4 v132, s[10:11]
	s_add_i32 m0, s45, 0x16000
	s_add_u32 s50, s6, s8
	s_addc_u32 s51, s7, s9
	s_add_u32 s50, s50, s101
	s_addc_u32 s51, s51, 0
	s_add_u32 s50, s50, 0xaa00000
	s_addc_u32 s51, s51, 0
	s_add_i32 s60, s45, 0x2000
	global_load_lds_dwordx4 v128, s[10:11]
	s_mov_b32 m0, s45
	s_add_u32 s8, s50, 0x40000
	global_load_lds_dwordx4 v134, s[50:51]
	s_mov_b32 m0, s60
	s_addc_u32 s9, s51, 0
	s_add_i32 s61, s45, 0x4000
	global_load_lds_dwordx4 v130, s[50:51]
	s_mov_b32 m0, s61
	s_add_i32 s63, s45, 0x6000
	global_load_lds_dwordx4 v134, s[8:9]
	s_mov_b32 m0, s63
	v_mov_b32_e32 v129, v133
	global_load_lds_dwordx4 v130, s[8:9]
	v_mov_b32_e32 v135, v133
	v_mov_b32_e32 v131, v133
	s_cmp_eq_u32 s4, 1
	v_lshl_add_u64 v[6:7], s[52:53], 0, v[132:133]
	v_lshl_add_u64 v[4:5], s[52:53], 0, v[128:129]
	v_lshl_add_u64 v[0:1], s[50:51], 0, v[134:135]
	s_cselect_b64 s[8:9], -1, 0
	s_cmp_lg_u32 s4, 1
	v_lshl_add_u64 v[2:3], s[50:51], 0, v[130:131]
	s_cbranch_scc1 .Lp5_741
	s_barrier
.Lp5_741:
	s_add_u32 s10, s6, 0xd200000
	s_addc_u32 s11, s7, 0
	s_lshl_b32 s5, s5, 5
	s_mov_b64 s[12:13], 0x80
	s_and_b32 s5, s5, 0x60
	s_add_i32 m0, s45, 0x18000
	v_lshl_add_u64 v[6:7], v[6:7], 0, s[12:13]
	s_lshl_b32 s17, s4, 13
	s_lshl_b32 s34, s5, 7
	s_waitcnt vmcnt(2)
	s_barrier
	global_load_lds_dwordx4 v[6:7], off
	v_lshl_add_u64 v[4:5], v[4:5], 0, s[12:13]
	s_add_i32 m0, s45, 0x1a000
	s_add_i32 s66, s45, 0x8000
	s_add_i32 s67, s45, 0xa000
	global_load_lds_dwordx4 v[4:5], off
	v_lshl_add_u64 v[0:1], v[0:1], 0, s[12:13]
	s_mov_b32 m0, s66
	s_add_u32 s18, s52, 0x40080
	global_load_lds_dwordx4 v[0:1], off
	v_lshl_add_u64 v[0:1], v[2:3], 0, s[12:13]
	s_mov_b32 m0, s67
	s_addc_u32 s19, s53, 0
	global_load_lds_dwordx4 v[0:1], off
	s_add_i32 m0, s45, 0x1c000
	v_lshl_add_u64 v[0:1], s[18:19], 0, v[132:133]
	global_load_lds_dwordx4 v[0:1], off
	v_lshl_add_u64 v[0:1], s[18:19], 0, v[128:129]
	s_add_i32 m0, s45, 0x1e000
	s_cmpk_lt_u32 s16, 0x100
	global_load_lds_dwordx4 v[0:1], off
	v_lshrrev_b32_e32 v1, 1, v8
	v_and_b32_e32 v1, 24, v1
	v_and_b32_e32 v0, 15, v8
	v_lshlrev_b32_e32 v2, 1, v1
	v_lshl_or_b32 v144, s4, 6, v0
	v_lshl_or_b32 v0, v0, 6, v2
	v_lshlrev_b32_e32 v2, 2, v8
	v_and_b32_e32 v2, 32, v2
	v_bitop3_b32 v3, v0, s17, v2 bitop3:0xde
	v_bitop3_b32 v145, v0, s34, v2 bitop3:0xde
	v_lshlrev_b32_e32 v0, 14, v13
	v_and_b32_e32 v0, 0xffff8000, v0
	v_or_b32_e32 v146, s5, v1
	v_lshl_add_u32 v0, v12, 11, v0
	v_and_b32_e32 v1, 1, v13
	v_lshl_or_b32 v0, v1, 6, v0
	v_lshl_add_u32 v136, v14, 1, v0
	v_lshlrev_b32_e32 v0, 14, v9
	v_and_b32_e32 v0, 0xffff8000, v0
	s_waitcnt vmcnt(6)
	v_lshl_add_u32 v0, v10, 11, v0
	v_and_b32_e32 v1, 1, v9
	s_cselect_b64 s[16:17], -1, 0
	v_lshl_or_b32 v0, v1, 6, v0
	s_add_i32 s71, 0, 0x10000
	s_add_i32 s72, 0, 0x14000
	s_mov_b32 s68, 0
	s_ashr_i32 s69, s22, 31
	s_mov_b32 s70, s22
	v_mov_b32_e32 v137, v133
	v_lshl_add_u32 v138, v11, 1, v0
	v_mov_b32_e32 v139, v133
	v_mov_b64_e32 v[140:141], 0x140
	v_mov_b64_e32 v[142:143], 0x13f
	v_add_u32_e32 v147, s71, v145
	v_add_u32_e32 v148, s72, v145
	v_add_u32_e32 v149, 0, v3
	s_mov_b64 s[18:19], 0x40000
	s_mov_b32 s73, 0x40000
	s_mov_b64 s[34:35], 0x48000
	s_mov_b32 s74, 0x48000
	s_mov_b64 s[36:37], 0x50000
	s_mov_b32 s75, 0x50000
	s_mov_b64 s[38:39], 0x58000
	s_mov_b32 s76, 0x58000
	s_barrier
	s_branch .Lp5_744

.Lp5_744:
	s_add_i32 s68, s68, 1
	s_mov_b64 s[4:5], 0
	s_cmp_eq_u32 s98, 3
	s_cbranch_scc1 .Lsk5_h3
	s_cmp_lt_u32 s68, 3
	s_cselect_b64 s[4:5], -1, 0
	s_lshr_b32 s40, s99, 3
	s_mul_i32 s40, s40, 10
	s_and_b32 s42, s99, 7
	s_add_i32 s40, s40, s42
	s_mov_b32 s42, s98
	s_cmp_eq_u32 s68, 1
	s_cselect_b32 s54, 0x200, 0
	s_cselect_b32 s101, 8, 0
	s_branch .Lsk5_hj
.Lsk5_h3:
	s_cmp_eq_u32 s68, 1
	s_cselect_b64 s[4:5], -1, 0
	s_lshr_b32 s40, s99, 3
	s_mul_i32 s40, s40, 10
	s_bfe_u32 s42, s99, 0x10002
	s_add_i32 s40, s40, s42
	s_add_i32 s40, s40, 8
	s_and_b32 s42, s99, 3
	s_movk_i32 s54, 0x600
	s_movk_i32 s101, 0
.Lsk5_hj:
.Lp5_746:
	s_ashr_i32 s41, s40, 31
	s_lshl_b64 s[46:47], s[40:41], 19
	s_add_u32 s46, s6, s46
	s_addc_u32 s47, s7, s47
	s_add_u32 s46, s46, s54
	s_addc_u32 s47, s47, 0
	s_add_u32 s46, s46, 0xaa00000
	s_addc_u32 s47, s47, 0
	s_and_b64 s[48:49], s[4:5], exec
	s_cselect_b32 s41, s47, s51
	s_cselect_b32 s78, s46, s50
	s_ashr_i32 s43, s42, 31
	s_lshl_b64 s[48:49], s[42:43], 19
	s_add_u32 s48, s56, s48
	s_addc_u32 s49, s57, s49
	s_add_u32 s48, s48, s54
	s_addc_u32 s49, s49, 0
	s_and_b64 s[54:55], s[4:5], exec
	s_cselect_b32 s43, s49, s53
	s_cselect_b32 s79, s48, s52
	s_add_u32 s50, s50, 0x40080
	s_addc_u32 s51, s51, 0
	s_add_u32 s80, s52, 0x100
	s_addc_u32 s81, s53, 0
	s_mov_b32 s82, -2
	s_cmp_lt_u32 s98, 3
	s_cbranch_scc0 .Lsk5_zero
	s_cmp_eq_u32 s68, 3
	s_cbranch_scc1 .Lp5_747

.Lp5_747:
	ds_read_b128 v[150:153], v147
	ds_read_b128 v[154:157], v147 offset:1024
	ds_read_b128 v[158:161], v147 offset:2048
	ds_read_b128 v[162:165], v147 offset:3072
	ds_read_b128 v[166:169], v148
	ds_read_b128 v[170:173], v148 offset:1024
	ds_read_b128 v[174:177], v148 offset:2048
	ds_read_b128 v[178:181], v148 offset:3072
	s_add_u32 s52, s50, 0xfffc0080
	s_addc_u32 s53, s51, -1
	s_cmp_eq_u32 s82, s100
	s_cselect_b32 s55, s41, s53
	s_cselect_b32 s54, s78, s52
	s_cselect_b32 s53, s43, s81
	s_cselect_b32 s52, s79, s80
	v_lshl_add_u64 v[186:187], s[50:51], 0, v[136:137]
	s_add_i32 m0, s45, 0xc000
	ds_read_b128 v[182:185], v149
	ds_read_b128 v[190:193], v149 offset:1024
	ds_read_b128 v[194:197], v149 offset:2048
	ds_read_b128 v[198:201], v149 offset:3072
	ds_read_b128 v[202:205], v149 offset:4096
	ds_read_b128 v[206:209], v149 offset:5120
	ds_read_b128 v[210:213], v149 offset:6144
	ds_read_b128 v[214:217], v149 offset:7168
	global_load_lds_dwordx4 v[186:187], off
	v_lshl_add_u64 v[186:187], s[50:51], 0, v[138:139]
	s_add_i32 m0, s45, 0xe000
	s_nop 0
	global_load_lds_dwordx4 v[186:187], off
	s_waitcnt vmcnt(8)
	s_waitcnt lgkmcnt(0)
	s_barrier
	s_setprio 1
	s_waitcnt lgkmcnt(0)
	v_mfma_f32_16x16x32_bf16 v[124:127], v[150:153], v[182:185], v[124:127]
	v_mfma_f32_16x16x32_bf16 v[120:123], v[158:161], v[182:185], v[120:123]
	v_mfma_f32_16x16x32_bf16 v[116:119], v[150:153], v[194:197], v[116:119]
	v_mfma_f32_16x16x32_bf16 v[112:115], v[158:161], v[194:197], v[112:115]
	v_mfma_f32_16x16x32_bf16 v[100:103], v[150:153], v[202:205], v[100:103]
	v_mfma_f32_16x16x32_bf16 v[96:99], v[158:161], v[202:205], v[96:99]
	v_mfma_f32_16x16x32_bf16 v[84:87], v[150:153], v[210:213], v[84:87]
	v_mfma_f32_16x16x32_bf16 v[80:83], v[158:161], v[210:213], v[80:83]
	v_mfma_f32_16x16x32_bf16 v[124:127], v[154:157], v[190:193], v[124:127]
	v_mfma_f32_16x16x32_bf16 v[120:123], v[162:165], v[190:193], v[120:123]
	v_mfma_f32_16x16x32_bf16 v[116:119], v[154:157], v[198:201], v[116:119]
	v_mfma_f32_16x16x32_bf16 v[112:115], v[162:165], v[198:201], v[112:115]
	v_mfma_f32_16x16x32_bf16 v[100:103], v[154:157], v[206:209], v[100:103]
	v_mfma_f32_16x16x32_bf16 v[96:99], v[162:165], v[206:209], v[96:99]
	v_mfma_f32_16x16x32_bf16 v[84:87], v[154:157], v[214:217], v[84:87]
	v_mfma_f32_16x16x32_bf16 v[80:83], v[162:165], v[214:217], v[80:83]
	s_setprio 0
	s_setprio 1
	v_mfma_f32_16x16x32_bf16 v[108:111], v[166:169], v[182:185], v[108:111]
	v_mfma_f32_16x16x32_bf16 v[104:107], v[174:177], v[182:185], v[104:107]
	v_mfma_f32_16x16x32_bf16 v[92:95], v[166:169], v[194:197], v[92:95]
	v_mfma_f32_16x16x32_bf16 v[88:91], v[174:177], v[194:197], v[88:91]
	v_mfma_f32_16x16x32_bf16 v[76:79], v[166:169], v[202:205], v[76:79]
	v_mfma_f32_16x16x32_bf16 v[72:75], v[174:177], v[202:205], v[72:75]
	v_mfma_f32_16x16x32_bf16 v[68:71], v[166:169], v[210:213], v[68:71]
	v_mfma_f32_16x16x32_bf16 v[64:67], v[174:177], v[210:213], v[64:67]
	v_mfma_f32_16x16x32_bf16 v[108:111], v[170:173], v[190:193], v[108:111]
	v_mfma_f32_16x16x32_bf16 v[104:107], v[178:181], v[190:193], v[104:107]
	v_mfma_f32_16x16x32_bf16 v[92:95], v[170:173], v[198:201], v[92:95]
	v_mfma_f32_16x16x32_bf16 v[88:91], v[178:181], v[198:201], v[88:91]
	v_mfma_f32_16x16x32_bf16 v[76:79], v[170:173], v[206:209], v[76:79]
	v_mfma_f32_16x16x32_bf16 v[72:75], v[178:181], v[206:209], v[72:75]
	v_mfma_f32_16x16x32_bf16 v[68:71], v[170:173], v[214:217], v[68:71]
	v_mfma_f32_16x16x32_bf16 v[64:67], v[178:181], v[214:217], v[64:67]
	s_setprio 0
	s_barrier
	s_add_i32 s62, s71, s58
	v_lshl_add_u64 v[186:187], s[52:53], 0, v[132:133]
	s_mov_b32 m0, s62
	ds_read_b128 v[182:185], v149 offset:16384
	ds_read_b128 v[190:193], v149 offset:17408
	ds_read_b128 v[194:197], v149 offset:18432
	ds_read_b128 v[198:201], v149 offset:19456
	ds_read_b128 v[202:205], v149 offset:20480
	ds_read_b128 v[206:209], v149 offset:21504
	ds_read_b128 v[210:213], v149 offset:22528
	ds_read_b128 v[214:217], v149 offset:23552
	global_load_lds_dwordx4 v[186:187], off
	s_add_i32 m0, s62, 0x2000
	s_add_u32 s84, s52, 0x40000
	v_lshl_add_u64 v[218:219], s[52:53], 0, v[128:129]
	s_addc_u32 s85, s53, 0
	s_add_i32 s62, s72, s58
	global_load_lds_dwordx4 v[218:219], off
	v_lshl_add_u64 v[220:221], s[84:85], 0, v[132:133]
	s_mov_b32 m0, s62
	v_lshl_add_u64 v[222:223], s[54:55], 0, v[130:131]
	global_load_lds_dwordx4 v[220:221], off
	v_lshl_add_u64 v[220:221], s[84:85], 0, v[128:129]
	s_add_i32 m0, s62, 0x2000
	s_nop 0
	global_load_lds_dwordx4 v[220:221], off
	v_lshl_add_u64 v[220:221], s[54:55], 0, v[134:135]
	s_mov_b32 m0, s45
	s_nop 0
	global_load_lds_dwordx4 v[220:221], off
	s_mov_b32 m0, s60
	s_nop 0
	global_load_lds_dwordx4 v[222:223], off
	s_waitcnt vmcnt(8)
	s_waitcnt lgkmcnt(0)
	s_barrier
	s_setprio 1
	s_waitcnt lgkmcnt(0)
	v_mfma_f32_16x16x32_bf16 v[60:63], v[150:153], v[182:185], v[60:63]
	v_mfma_f32_16x16x32_bf16 v[56:59], v[158:161], v[182:185], v[56:59]
	v_mfma_f32_16x16x32_bf16 v[52:55], v[150:153], v[194:197], v[52:55]
	v_mfma_f32_16x16x32_bf16 v[48:51], v[158:161], v[194:197], v[48:51]
	v_mfma_f32_16x16x32_bf16 v[36:39], v[150:153], v[202:205], v[36:39]
	v_mfma_f32_16x16x32_bf16 v[32:35], v[158:161], v[202:205], v[32:35]
	v_mfma_f32_16x16x32_bf16 v[20:23], v[150:153], v[210:213], v[20:23]
	v_mfma_f32_16x16x32_bf16 v[16:19], v[158:161], v[210:213], v[16:19]
	v_mfma_f32_16x16x32_bf16 v[60:63], v[154:157], v[190:193], v[60:63]
	v_mfma_f32_16x16x32_bf16 v[56:59], v[162:165], v[190:193], v[56:59]
	v_mfma_f32_16x16x32_bf16 v[52:55], v[154:157], v[198:201], v[52:55]
	v_mfma_f32_16x16x32_bf16 v[48:51], v[162:165], v[198:201], v[48:51]
	v_mfma_f32_16x16x32_bf16 v[36:39], v[154:157], v[206:209], v[36:39]
	v_mfma_f32_16x16x32_bf16 v[32:35], v[162:165], v[206:209], v[32:35]
	v_mfma_f32_16x16x32_bf16 v[20:23], v[154:157], v[214:217], v[20:23]
	v_mfma_f32_16x16x32_bf16 v[16:19], v[162:165], v[214:217], v[16:19]
	s_setprio 0
	s_setprio 1
	v_mfma_f32_16x16x32_bf16 v[44:47], v[166:169], v[182:185], v[44:47]
	v_mfma_f32_16x16x32_bf16 v[40:43], v[174:177], v[182:185], v[40:43]
	v_mfma_f32_16x16x32_bf16 v[28:31], v[166:169], v[194:197], v[28:31]
	v_mfma_f32_16x16x32_bf16 v[24:27], v[174:177], v[194:197], v[24:27]
	v_mfma_f32_16x16x32_bf16 v[12:15], v[166:169], v[202:205], v[12:15]
	v_mfma_f32_16x16x32_bf16 v[8:11], v[174:177], v[202:205], v[8:11]
	v_mfma_f32_16x16x32_bf16 v[4:7], v[166:169], v[210:213], v[4:7]
	v_mfma_f32_16x16x32_bf16 v[0:3], v[174:177], v[210:213], v[0:3]
	v_mfma_f32_16x16x32_bf16 v[44:47], v[170:173], v[190:193], v[44:47]
	v_mfma_f32_16x16x32_bf16 v[40:43], v[178:181], v[190:193], v[40:43]
	v_mfma_f32_16x16x32_bf16 v[28:31], v[170:173], v[198:201], v[28:31]
	v_mfma_f32_16x16x32_bf16 v[24:27], v[178:181], v[198:201], v[24:27]
	v_mfma_f32_16x16x32_bf16 v[12:15], v[170:173], v[206:209], v[12:15]
	v_mfma_f32_16x16x32_bf16 v[8:11], v[178:181], v[206:209], v[8:11]
	v_mfma_f32_16x16x32_bf16 v[4:7], v[170:173], v[214:217], v[4:7]
	v_mfma_f32_16x16x32_bf16 v[0:3], v[178:181], v[214:217], v[0:3]
	s_setprio 0
	s_barrier
	s_add_i32 s62, 0, 0x18000
	s_add_i32 s64, 0, 0x1c000
	v_add_u32_e32 v162, s62, v145
	v_add_u32_e32 v178, s64, v145
	ds_read_b128 v[150:153], v162
	ds_read_b128 v[154:157], v162 offset:1024
	ds_read_b128 v[158:161], v162 offset:2048
	ds_read_b128 v[162:165], v162 offset:3072
	ds_read_b128 v[166:169], v178
	ds_read_b128 v[170:173], v178 offset:1024
	ds_read_b128 v[174:177], v178 offset:2048
	ds_read_b128 v[178:181], v178 offset:3072
	s_add_u32 s54, s54, 0x40000
	s_addc_u32 s55, s55, 0
	s_mov_b32 m0, s61
	v_lshl_add_u64 v[224:225], s[54:55], 0, v[134:135]
	ds_read_b128 v[182:185], v149 offset:32768
	ds_read_b128 v[190:193], v149 offset:33792
	ds_read_b128 v[194:197], v149 offset:34816
	ds_read_b128 v[198:201], v149 offset:35840
	ds_read_b128 v[202:205], v149 offset:36864
	ds_read_b128 v[206:209], v149 offset:37888
	ds_read_b128 v[210:213], v149 offset:38912
	ds_read_b128 v[214:217], v149 offset:39936
	global_load_lds_dwordx4 v[224:225], off
	v_lshl_add_u64 v[224:225], s[54:55], 0, v[130:131]
	s_mov_b32 m0, s63
	s_nop 0
	global_load_lds_dwordx4 v[224:225], off
	s_waitcnt vmcnt(8)
	s_waitcnt lgkmcnt(0)
	s_barrier
	s_setprio 1
	s_waitcnt lgkmcnt(0)
	v_mfma_f32_16x16x32_bf16 v[124:127], v[150:153], v[182:185], v[124:127]
	v_mfma_f32_16x16x32_bf16 v[120:123], v[158:161], v[182:185], v[120:123]
	v_mfma_f32_16x16x32_bf16 v[116:119], v[150:153], v[194:197], v[116:119]
	v_mfma_f32_16x16x32_bf16 v[112:115], v[158:161], v[194:197], v[112:115]
	v_mfma_f32_16x16x32_bf16 v[100:103], v[150:153], v[202:205], v[100:103]
	v_mfma_f32_16x16x32_bf16 v[96:99], v[158:161], v[202:205], v[96:99]
	v_mfma_f32_16x16x32_bf16 v[84:87], v[150:153], v[210:213], v[84:87]
	v_mfma_f32_16x16x32_bf16 v[80:83], v[158:161], v[210:213], v[80:83]
	v_mfma_f32_16x16x32_bf16 v[124:127], v[154:157], v[190:193], v[124:127]
	v_mfma_f32_16x16x32_bf16 v[120:123], v[162:165], v[190:193], v[120:123]
	v_mfma_f32_16x16x32_bf16 v[116:119], v[154:157], v[198:201], v[116:119]
	v_mfma_f32_16x16x32_bf16 v[112:115], v[162:165], v[198:201], v[112:115]
	v_mfma_f32_16x16x32_bf16 v[100:103], v[154:157], v[206:209], v[100:103]
	v_mfma_f32_16x16x32_bf16 v[96:99], v[162:165], v[206:209], v[96:99]
	v_mfma_f32_16x16x32_bf16 v[84:87], v[154:157], v[214:217], v[84:87]
	v_mfma_f32_16x16x32_bf16 v[80:83], v[162:165], v[214:217], v[80:83]
	s_setprio 0
	s_setprio 1
	v_mfma_f32_16x16x32_bf16 v[108:111], v[166:169], v[182:185], v[108:111]
	v_mfma_f32_16x16x32_bf16 v[104:107], v[174:177], v[182:185], v[104:107]
	v_mfma_f32_16x16x32_bf16 v[92:95], v[166:169], v[194:197], v[92:95]
	v_mfma_f32_16x16x32_bf16 v[88:91], v[174:177], v[194:197], v[88:91]
	v_mfma_f32_16x16x32_bf16 v[76:79], v[166:169], v[202:205], v[76:79]
	v_mfma_f32_16x16x32_bf16 v[72:75], v[174:177], v[202:205], v[72:75]
	v_mfma_f32_16x16x32_bf16 v[68:71], v[166:169], v[210:213], v[68:71]
	v_mfma_f32_16x16x32_bf16 v[64:67], v[174:177], v[210:213], v[64:67]
	v_mfma_f32_16x16x32_bf16 v[108:111], v[170:173], v[190:193], v[108:111]
	v_mfma_f32_16x16x32_bf16 v[104:107], v[178:181], v[190:193], v[104:107]
	v_mfma_f32_16x16x32_bf16 v[92:95], v[170:173], v[198:201], v[92:95]
	v_mfma_f32_16x16x32_bf16 v[88:91], v[178:181], v[198:201], v[88:91]
	v_mfma_f32_16x16x32_bf16 v[76:79], v[170:173], v[206:209], v[76:79]
	v_mfma_f32_16x16x32_bf16 v[72:75], v[178:181], v[206:209], v[72:75]
	v_mfma_f32_16x16x32_bf16 v[68:71], v[170:173], v[214:217], v[68:71]
	v_mfma_f32_16x16x32_bf16 v[64:67], v[178:181], v[214:217], v[64:67]
	s_setprio 0
	s_barrier
	s_add_i32 s54, s62, s58
	v_lshl_add_u64 v[186:187], v[186:187], 0, s[12:13]
	s_mov_b32 m0, s54
	ds_read_b128 v[182:185], v149 offset:49152
	ds_read_b128 v[190:193], v149 offset:50176
	ds_read_b128 v[194:197], v149 offset:51200
	ds_read_b128 v[198:201], v149 offset:52224
	ds_read_b128 v[202:205], v149 offset:53248
	ds_read_b128 v[206:209], v149 offset:54272
	ds_read_b128 v[210:213], v149 offset:55296
	ds_read_b128 v[214:217], v149 offset:56320
	global_load_lds_dwordx4 v[186:187], off
	s_add_i32 m0, s54, 0x2000
	s_add_u32 s52, s52, 0x40080
	v_lshl_add_u64 v[186:187], v[218:219], 0, s[12:13]
	s_addc_u32 s53, s53, 0
	s_add_i32 s54, s64, s58
	global_load_lds_dwordx4 v[186:187], off
	v_lshl_add_u64 v[186:187], s[52:53], 0, v[132:133]
	s_mov_b32 m0, s54
	s_nop 0
	global_load_lds_dwordx4 v[186:187], off
	v_lshl_add_u64 v[186:187], s[52:53], 0, v[128:129]
	s_add_i32 m0, s54, 0x2000
	s_nop 0
	global_load_lds_dwordx4 v[186:187], off
	v_lshl_add_u64 v[186:187], v[220:221], 0, s[12:13]
	s_mov_b32 m0, s66
	s_nop 0
	global_load_lds_dwordx4 v[186:187], off
	v_lshl_add_u64 v[186:187], v[222:223], 0, s[12:13]
	s_mov_b32 m0, s67
	s_nop 0
	global_load_lds_dwordx4 v[186:187], off
	s_waitcnt vmcnt(8)
	s_waitcnt lgkmcnt(0)
	s_barrier
	s_setprio 1
	s_waitcnt lgkmcnt(0)
	v_mfma_f32_16x16x32_bf16 v[60:63], v[150:153], v[182:185], v[60:63]
	v_mfma_f32_16x16x32_bf16 v[56:59], v[158:161], v[182:185], v[56:59]
	v_mfma_f32_16x16x32_bf16 v[52:55], v[150:153], v[194:197], v[52:55]
	v_mfma_f32_16x16x32_bf16 v[48:51], v[158:161], v[194:197], v[48:51]
	v_mfma_f32_16x16x32_bf16 v[36:39], v[150:153], v[202:205], v[36:39]
	v_mfma_f32_16x16x32_bf16 v[32:35], v[158:161], v[202:205], v[32:35]
	v_mfma_f32_16x16x32_bf16 v[20:23], v[150:153], v[210:213], v[20:23]
	v_mfma_f32_16x16x32_bf16 v[16:19], v[158:161], v[210:213], v[16:19]
	v_mfma_f32_16x16x32_bf16 v[60:63], v[154:157], v[190:193], v[60:63]
	v_mfma_f32_16x16x32_bf16 v[56:59], v[162:165], v[190:193], v[56:59]
	v_mfma_f32_16x16x32_bf16 v[52:55], v[154:157], v[198:201], v[52:55]
	v_mfma_f32_16x16x32_bf16 v[48:51], v[162:165], v[198:201], v[48:51]
	v_mfma_f32_16x16x32_bf16 v[36:39], v[154:157], v[206:209], v[36:39]
	v_mfma_f32_16x16x32_bf16 v[32:35], v[162:165], v[206:209], v[32:35]
	v_mfma_f32_16x16x32_bf16 v[20:23], v[154:157], v[214:217], v[20:23]
	v_mfma_f32_16x16x32_bf16 v[16:19], v[162:165], v[214:217], v[16:19]
	s_setprio 0
	s_setprio 1
	v_mfma_f32_16x16x32_bf16 v[44:47], v[166:169], v[182:185], v[44:47]
	v_mfma_f32_16x16x32_bf16 v[40:43], v[174:177], v[182:185], v[40:43]
	v_mfma_f32_16x16x32_bf16 v[28:31], v[166:169], v[194:197], v[28:31]
	v_mfma_f32_16x16x32_bf16 v[24:27], v[174:177], v[194:197], v[24:27]
	v_mfma_f32_16x16x32_bf16 v[12:15], v[166:169], v[202:205], v[12:15]
	v_mfma_f32_16x16x32_bf16 v[8:11], v[174:177], v[202:205], v[8:11]
	v_mfma_f32_16x16x32_bf16 v[4:7], v[166:169], v[210:213], v[4:7]
	v_mfma_f32_16x16x32_bf16 v[0:3], v[174:177], v[210:213], v[0:3]
	v_mfma_f32_16x16x32_bf16 v[44:47], v[170:173], v[190:193], v[44:47]
	v_mfma_f32_16x16x32_bf16 v[40:43], v[178:181], v[190:193], v[40:43]
	v_mfma_f32_16x16x32_bf16 v[28:31], v[170:173], v[198:201], v[28:31]
	v_mfma_f32_16x16x32_bf16 v[24:27], v[178:181], v[198:201], v[24:27]
	v_mfma_f32_16x16x32_bf16 v[12:15], v[170:173], v[206:209], v[12:15]
	v_mfma_f32_16x16x32_bf16 v[8:11], v[178:181], v[206:209], v[8:11]
	v_mfma_f32_16x16x32_bf16 v[4:7], v[170:173], v[214:217], v[4:7]
	v_mfma_f32_16x16x32_bf16 v[0:3], v[178:181], v[214:217], v[0:3]
	s_setprio 0
	s_barrier
	s_add_i32 s82, s82, 2
	s_add_u32 s50, s50, 0x100
	s_addc_u32 s51, s51, 0
	s_add_u32 s80, s80, 0x100
	s_addc_u32 s81, s81, 0
	s_cmp_gt_u32 s82, s100
	s_cbranch_scc0 .Lp5_747
	s_cmp_lt_u32 s98, 3
	s_cbranch_scc0 .Lsk5_notc
	s_cmp_eq_u32 s68, 2
	s_cbranch_scc1 .Lp5_742

.Lsk5_pstore:
	s_mul_i32 s54, s99, 3
	s_add_i32 s54, s54, s98
	s_lshl_b32 s55, s54, 2
	s_lshl_b32 s54, s54, 18
	s_add_u32 s84, s6, 0x0
	s_addc_u32 s85, s7, 0
	s_add_u32 s84, s84, s54
	s_addc_u32 s85, s85, 0
	s_movk_i32 s62, 0x2000
	v_lshlrev_b32_e32 v150, 4, v188
	global_store_dwordx4 v150, v[0:3], s[84:85] sc1
	s_add_u32 s84, s84, s62
	s_addc_u32 s85, s85, 0
	global_store_dwordx4 v150, v[4:7], s[84:85] sc1
	s_add_u32 s84, s84, s62
	s_addc_u32 s85, s85, 0
	global_store_dwordx4 v150, v[8:11], s[84:85] sc1
	s_add_u32 s84, s84, s62
	s_addc_u32 s85, s85, 0
	global_store_dwordx4 v150, v[12:15], s[84:85] sc1
	s_add_u32 s84, s84, s62
	s_addc_u32 s85, s85, 0
	global_store_dwordx4 v150, v[16:19], s[84:85] sc1
	s_add_u32 s84, s84, s62
	s_addc_u32 s85, s85, 0
	global_store_dwordx4 v150, v[20:23], s[84:85] sc1
	s_add_u32 s84, s84, s62
	s_addc_u32 s85, s85, 0
	global_store_dwordx4 v150, v[24:27], s[84:85] sc1
	s_add_u32 s84, s84, s62
	s_addc_u32 s85, s85, 0
	global_store_dwordx4 v150, v[28:31], s[84:85] sc1
	s_add_u32 s84, s84, s62
	s_addc_u32 s85, s85, 0
	global_store_dwordx4 v150, v[32:35], s[84:85] sc1
	s_add_u32 s84, s84, s62
	s_addc_u32 s85, s85, 0
	global_store_dwordx4 v150, v[36:39], s[84:85] sc1
	s_add_u32 s84, s84, s62
	s_addc_u32 s85, s85, 0
	global_store_dwordx4 v150, v[40:43], s[84:85] sc1
	s_add_u32 s84, s84, s62
	s_addc_u32 s85, s85, 0
	global_store_dwordx4 v150, v[44:47], s[84:85] sc1
	s_add_u32 s84, s84, s62
	s_addc_u32 s85, s85, 0
	global_store_dwordx4 v150, v[48:51], s[84:85] sc1
	s_add_u32 s84, s84, s62
	s_addc_u32 s85, s85, 0
	global_store_dwordx4 v150, v[52:55], s[84:85] sc1
	s_add_u32 s84, s84, s62
	s_addc_u32 s85, s85, 0
	global_store_dwordx4 v150, v[56:59], s[84:85] sc1
	s_add_u32 s84, s84, s62
	s_addc_u32 s85, s85, 0
	global_store_dwordx4 v150, v[60:63], s[84:85] sc1
	s_add_u32 s84, s84, s62
	s_addc_u32 s85, s85, 0
	global_store_dwordx4 v150, v[64:67], s[84:85] sc1
	s_add_u32 s84, s84, s62
	s_addc_u32 s85, s85, 0
	global_store_dwordx4 v150, v[68:71], s[84:85] sc1
	s_add_u32 s84, s84, s62
	s_addc_u32 s85, s85, 0
	global_store_dwordx4 v150, v[72:75], s[84:85] sc1
	s_add_u32 s84, s84, s62
	s_addc_u32 s85, s85, 0
	global_store_dwordx4 v150, v[76:79], s[84:85] sc1
	s_add_u32 s84, s84, s62
	s_addc_u32 s85, s85, 0
	global_store_dwordx4 v150, v[80:83], s[84:85] sc1
	s_add_u32 s84, s84, s62
	s_addc_u32 s85, s85, 0
	global_store_dwordx4 v150, v[84:87], s[84:85] sc1
	s_add_u32 s84, s84, s62
	s_addc_u32 s85, s85, 0
	global_store_dwordx4 v150, v[88:91], s[84:85] sc1
	s_add_u32 s84, s84, s62
	s_addc_u32 s85, s85, 0
	global_store_dwordx4 v150, v[92:95], s[84:85] sc1
	s_add_u32 s84, s84, s62
	s_addc_u32 s85, s85, 0
	global_store_dwordx4 v150, v[96:99], s[84:85] sc1
	s_add_u32 s84, s84, s62
	s_addc_u32 s85, s85, 0
	global_store_dwordx4 v150, v[100:103], s[84:85] sc1
	s_add_u32 s84, s84, s62
	s_addc_u32 s85, s85, 0
	global_store_dwordx4 v150, v[104:107], s[84:85] sc1
	s_add_u32 s84, s84, s62
	s_addc_u32 s85, s85, 0
	global_store_dwordx4 v150, v[108:111], s[84:85] sc1
	s_add_u32 s84, s84, s62
	s_addc_u32 s85, s85, 0
	global_store_dwordx4 v150, v[112:115], s[84:85] sc1
	s_add_u32 s84, s84, s62
	s_addc_u32 s85, s85, 0
	global_store_dwordx4 v150, v[116:119], s[84:85] sc1
	s_add_u32 s84, s84, s62
	s_addc_u32 s85, s85, 0
	global_store_dwordx4 v150, v[120:123], s[84:85] sc1
	s_add_u32 s84, s84, s62
	s_addc_u32 s85, s85, 0
	global_store_dwordx4 v150, v[124:127], s[84:85] sc1
	s_waitcnt vmcnt(0)
	s_barrier
	s_and_saveexec_b64 s[80:81], s[14:15]
	s_cbranch_execz .Lsk5_pdone
	v_mov_b32_e32 v151, 1
	v_mov_b32_e32 v152, s55
	v_add_u32_e32 v152, 0x3c00, v152
	global_store_dword v152, v151, s[24:25] sc1

.Lsk5_rload:
	s_mul_i32 s54, s99, 3
	s_lshl_b32 s55, s54, 2
	s_lshl_b32 s54, s54, 18
	s_add_u32 s84, s6, 0x0
	s_addc_u32 s85, s7, 0
	s_add_u32 s84, s84, s54
	s_addc_u32 s85, s85, 0
	s_movk_i32 s62, 0x2000
	v_lshlrev_b32_e32 v150, 4, v188
	s_and_saveexec_b64 s[80:81], s[14:15]
	s_cbranch_execz .Lsk5_polled
	v_mov_b32_e32 v152, s55
	v_add_u32_e32 v152, 0x3c00, v152
	s_mov_b32 s64, 0
.Lsk5_poll:
	global_load_dword v151, v152, s[24:25] sc1
	global_load_dword v153, v152, s[24:25] offset:4 sc1
	global_load_dword v154, v152, s[24:25] offset:8 sc1
	s_waitcnt vmcnt(0)
	v_and_b32_e32 v151, v151, v153
	v_and_b32_e32 v151, v151, v154
	s_nop 0
	v_readfirstlane_b32 s54, v151
	s_and_b32 s54, s54, 1
	s_cmp_lg_u32 s54, 0
	s_cbranch_scc1 .Lsk5_polled
	s_sleep 1
	s_add_i32 s64, s64, 1
	s_cmp_lt_u32 s64, 0x4000
	s_cbranch_scc1 .Lsk5_poll

.LBB0_1135:
	s_or_b64 exec, exec, s[2:3]
	s_mov_b64 s[8:9], s[0:1]
	s_waitcnt lgkmcnt(0)
	v_mov_b32_e32 v0, v188
	s_barrier
	s_add_i32 s4, 0, 0x24ffc
	v_mov_b32_e32 v0, s4
	ds_read_b32 v0, v0
	s_movk_i32 s4, 0x13f
	v_mov_b32_e32 v8, v188
	s_waitcnt lgkmcnt(0)
	v_cmp_lt_i32_e32 vcc, s4, v0
	v_readfirstlane_b32 s27, v0
	v_readfirstlane_b32 s16, v8
	s_cbranch_vccnz .Lp13_754
	v_lshlrev_b32_e32 v0, 4, v8
	v_add_u32_e32 v1, 0x2000, v0
	v_ashrrev_i32_e32 v2, 31, v1
	v_lshrrev_b32_e32 v2, 22, v2
	v_add_u32_e32 v2, v1, v2
	v_ashrrev_i32_e32 v9, 10, v2
	v_mul_i32_i24_e32 v2, 0x400, v9
	v_sub_u32_e32 v1, v1, v2
	v_lshrrev_b32_e32 v2, 4, v1
	v_bitop3_b32 v1, v2, v1, 32 bitop3:0x6c
	v_ashrrev_i32_e32 v2, 31, v1
	v_lshrrev_b32_e32 v2, 26, v2
	v_add_u32_e32 v2, v1, v2
	v_lshlrev_b32_e32 v3, 3, v9
	v_ashrrev_i32_e32 v10, 6, v2
	v_and_b32_e32 v3, -16, v3
	v_add_u32_e32 v3, v10, v3
	s_load_dwordx4 s[4:7], s[8:9], 0xa8
	v_and_b32_e32 v4, 3, v10
	s_mov_b32 s8, 0x1fffe0
	v_lshrrev_b32_e32 v5, 2, v3
	v_lshlrev_b32_e32 v6, 1, v3
	v_and_b32_e32 v2, 0xc0, v2
	v_and_or_b32 v4, v3, s8, v4
	v_and_b32_e32 v5, 4, v5
	v_and_b32_e32 v6, 24, v6
	v_sub_u32_e32 v1, v1, v2
	v_mov_b32_e32 v2, 1
	v_or3_b32 v4, v4, v5, v6
	v_lshlrev_b32_e32 v5, 5, v9
	v_ashrrev_i16_sdwa v1, v2, sext(v1) dst_sel:DWORD dst_unused:UNUSED_PAD src0_sel:DWORD src1_sel:BYTE_0
	v_and_b32_e32 v5, 32, v5
	v_bfe_i32 v11, v1, 0, 16
	v_add_lshl_u32 v1, v5, v11, 1
	v_lshl_add_u32 v128, v4, 11, v1
	v_lshl_add_u32 v130, v3, 11, v1
	v_bfe_i32 v1, v8, 27, 1
	v_lshrrev_b32_e32 v1, 22, v1
	v_add_u32_e32 v1, v0, v1
	v_and_b32_e32 v1, 0xfffffc00, v1
	v_sub_u32_e32 v0, v0, v1
	v_lshrrev_b32_e32 v1, 4, v0
	v_ashrrev_i32_e32 v3, 31, v8
	v_bitop3_b32 v0, v1, v0, 32 bitop3:0x6c
	v_lshrrev_b32_e32 v3, 26, v3
	v_ashrrev_i32_e32 v1, 31, v0
	v_add_u32_e32 v3, v8, v3
	v_lshrrev_b32_e32 v1, 26, v1
	v_ashrrev_i32_e32 v13, 6, v3
	v_add_u32_e32 v1, v0, v1
	v_lshlrev_b32_e32 v3, 3, v13
	s_waitcnt lgkmcnt(0)
	s_add_u32 s56, s6, 0xfc00000
	v_ashrrev_i32_e32 v12, 6, v1
	v_and_b32_e32 v3, -16, v3
	s_addc_u32 s57, s7, 0
	v_add_u32_e32 v3, v12, v3
	v_and_b32_e32 v4, 3, v12
	s_ashr_i32 s59, s27, 31
	v_and_or_b32 v4, v3, s8, v4
	s_and_b32 s8, s27, 7
	s_lshr_b32 s9, s27, 3
	s_and_b32 s98, s9, 3
	s_lshr_b32 s9, s9, 2
	s_lshl_b32 s99, s8, 3
	s_add_i32 s99, s99, s9
	s_mul_i32 s8, s8, 10
	s_cmp_eq_u32 s98, 3
	s_cbranch_scc1 .Lsk13_q3a
	s_lshr_b32 s10, s9, 2
	s_add_i32 s8, s8, s10
	s_add_i32 s8, s8, 8
	s_and_b32 s9, s9, 3
	s_lshl_b32 s10, s98, 9
	s_movk_i32 s100, 0
	s_branch .Lsk13_q3b

.Lsk13_q3b:
	s_lshl_b32 s8, s8, 2
	s_or_b32 s8, s8, s9
	s_mov_b32 s101, s10
	s_ashr_i32 s5, s16, 6
	s_ashr_i32 s4, s16, 8
	s_lshl_b32 s58, s5, 10
	v_lshrrev_b32_e32 v5, 2, v3
	v_lshlrev_b32_e32 v6, 1, v3
	v_and_b32_e32 v1, 0xc0, v1
	s_ashr_i32 s44, s8, 2
	v_and_b32_e32 v5, 4, v5
	v_and_b32_e32 v6, 24, v6
	v_sub_u32_e32 v0, v0, v1
	s_and_b32 s77, s8, 3
	s_ashr_i32 s45, s44, 31
	v_or3_b32 v4, v4, v5, v6
	v_lshlrev_b32_e32 v5, 5, v13
	v_ashrrev_i16_sdwa v0, v2, sext(v0) dst_sel:DWORD dst_unused:UNUSED_PAD src0_sel:DWORD src1_sel:BYTE_0
	s_lshl_b64 s[8:9], s[44:45], 19
	s_lshl_b32 s10, s77, 19
	s_add_u32 s10, s10, s101
	v_and_b32_e32 v5, 32, v5
	v_bfe_i32 v14, v0, 0, 16
	s_add_u32 s52, s56, s10
	v_add_lshl_u32 v0, v5, v14, 1
	s_addc_u32 s53, s57, 0
	s_add_i32 s45, s58, 0
	v_lshl_add_u32 v132, v4, 11, v0
	s_add_i32 m0, s45, 0x10000
	v_lshl_add_u32 v134, v3, 11, v0
	global_load_lds_dwordx4 v132, s[52:53]
	s_add_i32 m0, s45, 0x12000
	s_add_u32 s10, s52, 0x40000
	global_load_lds_dwordx4 v128, s[52:53]
	s_addc_u32 s11, s53, 0
	s_add_i32 m0, s45, 0x14000
	v_mov_b32_e32 v133, 0
	global_load_lds_dwordx4 v132, s[10:11]
	s_add_i32 m0, s45, 0x16000
	s_add_u32 s50, s6, s8
	s_addc_u32 s51, s7, s9
	s_add_u32 s50, s50, s101
	s_addc_u32 s51, s51, 0
	s_add_u32 s50, s50, 0xc800000
	s_addc_u32 s51, s51, 0
	s_add_i32 s60, s45, 0x2000
	global_load_lds_dwordx4 v128, s[10:11]
	s_mov_b32 m0, s45
	s_add_u32 s8, s50, 0x40000
	global_load_lds_dwordx4 v134, s[50:51]
	s_mov_b32 m0, s60
	s_addc_u32 s9, s51, 0
	s_add_i32 s61, s45, 0x4000
	global_load_lds_dwordx4 v130, s[50:51]
	s_mov_b32 m0, s61
	s_add_i32 s63, s45, 0x6000
	global_load_lds_dwordx4 v134, s[8:9]
	s_mov_b32 m0, s63
	v_mov_b32_e32 v129, v133
	global_load_lds_dwordx4 v130, s[8:9]
	v_mov_b32_e32 v135, v133
	v_mov_b32_e32 v131, v133
	s_cmp_eq_u32 s4, 1
	v_lshl_add_u64 v[6:7], s[52:53], 0, v[132:133]
	v_lshl_add_u64 v[4:5], s[52:53], 0, v[128:129]
	v_lshl_add_u64 v[0:1], s[50:51], 0, v[134:135]
	s_cselect_b64 s[8:9], -1, 0
	s_cmp_lg_u32 s4, 1
	v_lshl_add_u64 v[2:3], s[50:51], 0, v[130:131]
	s_cbranch_scc1 .Lp13_741
	s_barrier
.Lp13_741:
	s_add_u32 s10, s6, 0x0
	s_addc_u32 s11, s7, 0
	s_lshl_b32 s5, s5, 5
	s_mov_b64 s[12:13], 0x80
	s_and_b32 s5, s5, 0x60
	s_add_i32 m0, s45, 0x18000
	v_lshl_add_u64 v[6:7], v[6:7], 0, s[12:13]
	s_lshl_b32 s17, s4, 13
	s_lshl_b32 s34, s5, 7
	s_waitcnt vmcnt(2)
	s_barrier
	global_load_lds_dwordx4 v[6:7], off
	v_lshl_add_u64 v[4:5], v[4:5], 0, s[12:13]
	s_add_i32 m0, s45, 0x1a000
	s_add_i32 s66, s45, 0x8000
	s_add_i32 s67, s45, 0xa000
	global_load_lds_dwordx4 v[4:5], off
	v_lshl_add_u64 v[0:1], v[0:1], 0, s[12:13]
	s_mov_b32 m0, s66
	s_add_u32 s18, s52, 0x40080
	global_load_lds_dwordx4 v[0:1], off
	v_lshl_add_u64 v[0:1], v[2:3], 0, s[12:13]
	s_mov_b32 m0, s67
	s_addc_u32 s19, s53, 0
	global_load_lds_dwordx4 v[0:1], off
	s_add_i32 m0, s45, 0x1c000
	v_lshl_add_u64 v[0:1], s[18:19], 0, v[132:133]
	global_load_lds_dwordx4 v[0:1], off
	v_lshl_add_u64 v[0:1], s[18:19], 0, v[128:129]
	s_add_i32 m0, s45, 0x1e000
	s_cmpk_lt_u32 s16, 0x100
	global_load_lds_dwordx4 v[0:1], off
	v_lshrrev_b32_e32 v1, 1, v8
	v_and_b32_e32 v1, 24, v1
	v_and_b32_e32 v0, 15, v8
	v_lshlrev_b32_e32 v2, 1, v1
	v_lshl_or_b32 v144, s4, 6, v0
	v_lshl_or_b32 v0, v0, 6, v2
	v_lshlrev_b32_e32 v2, 2, v8
	v_and_b32_e32 v2, 32, v2
	v_bitop3_b32 v3, v0, s17, v2 bitop3:0xde
	v_bitop3_b32 v145, v0, s34, v2 bitop3:0xde
	v_lshlrev_b32_e32 v0, 14, v13
	v_and_b32_e32 v0, 0xffff8000, v0
	v_or_b32_e32 v146, s5, v1
	v_lshl_add_u32 v0, v12, 11, v0
	v_and_b32_e32 v1, 1, v13
	v_lshl_or_b32 v0, v1, 6, v0
	v_lshl_add_u32 v136, v14, 1, v0
	v_lshlrev_b32_e32 v0, 14, v9
	v_and_b32_e32 v0, 0xffff8000, v0
	s_waitcnt vmcnt(6)
	v_lshl_add_u32 v0, v10, 11, v0
	v_and_b32_e32 v1, 1, v9
	s_cselect_b64 s[16:17], -1, 0
	v_lshl_or_b32 v0, v1, 6, v0
	s_add_i32 s71, 0, 0x10000
	s_add_i32 s72, 0, 0x14000
	s_mov_b32 s68, 0
	s_ashr_i32 s69, s22, 31
	s_mov_b32 s70, s22
	v_mov_b32_e32 v137, v133
	v_lshl_add_u32 v138, v11, 1, v0
	v_mov_b32_e32 v139, v133
	v_mov_b64_e32 v[140:141], 0x140
	v_mov_b64_e32 v[142:143], 0x13f
	v_add_u32_e32 v147, s71, v145
	v_add_u32_e32 v148, s72, v145
	v_add_u32_e32 v149, 0, v3
	s_mov_b64 s[18:19], 0x40000
	s_mov_b32 s73, 0x40000
	s_mov_b64 s[34:35], 0x48000
	s_mov_b32 s74, 0x48000
	s_mov_b64 s[36:37], 0x50000
	s_mov_b32 s75, 0x50000
	s_mov_b64 s[38:39], 0x58000
	s_mov_b32 s76, 0x58000
	s_barrier
	s_branch .Lp13_744

.Lsk13_hj:
.Lp13_746:
	s_ashr_i32 s41, s40, 31
	s_lshl_b64 s[46:47], s[40:41], 19
	s_add_u32 s46, s6, s46
	s_addc_u32 s47, s7, s47
	s_add_u32 s46, s46, s54
	s_addc_u32 s47, s47, 0
	s_add_u32 s46, s46, 0xc800000
	s_addc_u32 s47, s47, 0
	s_and_b64 s[48:49], s[4:5], exec
	s_cselect_b32 s41, s47, s51
	s_cselect_b32 s78, s46, s50
	s_ashr_i32 s43, s42, 31
	s_lshl_b64 s[48:49], s[42:43], 19
	s_add_u32 s48, s56, s48
	s_addc_u32 s49, s57, s49
	s_add_u32 s48, s48, s54
	s_addc_u32 s49, s49, 0
	s_and_b64 s[54:55], s[4:5], exec
	s_cselect_b32 s43, s49, s53
	s_cselect_b32 s79, s48, s52
	s_add_u32 s50, s50, 0x40080
	s_addc_u32 s51, s51, 0
	s_add_u32 s80, s52, 0x100
	s_addc_u32 s81, s53, 0
	s_mov_b32 s82, -2
	s_cmp_lt_u32 s98, 3
	s_cbranch_scc0 .Lsk13_zero
	s_cmp_eq_u32 s68, 3
	s_cbranch_scc1 .Lp13_747

.Lsk13_pstore:
	s_mul_i32 s54, s99, 3
	s_add_i32 s54, s54, s98
	s_lshl_b32 s55, s54, 2
	s_lshl_b32 s54, s54, 18
	s_add_u32 s84, s6, 0x4000000
	s_addc_u32 s85, s7, 0
	s_add_u32 s84, s84, s54
	s_addc_u32 s85, s85, 0
	s_movk_i32 s62, 0x2000
	v_lshlrev_b32_e32 v150, 4, v188
	global_store_dwordx4 v150, v[0:3], s[84:85] sc1
	s_add_u32 s84, s84, s62
	s_addc_u32 s85, s85, 0
	global_store_dwordx4 v150, v[4:7], s[84:85] sc1
	s_add_u32 s84, s84, s62
	s_addc_u32 s85, s85, 0
	global_store_dwordx4 v150, v[8:11], s[84:85] sc1
	s_add_u32 s84, s84, s62
	s_addc_u32 s85, s85, 0
	global_store_dwordx4 v150, v[12:15], s[84:85] sc1
	s_add_u32 s84, s84, s62
	s_addc_u32 s85, s85, 0
	global_store_dwordx4 v150, v[16:19], s[84:85] sc1
	s_add_u32 s84, s84, s62
	s_addc_u32 s85, s85, 0
	global_store_dwordx4 v150, v[20:23], s[84:85] sc1
	s_add_u32 s84, s84, s62
	s_addc_u32 s85, s85, 0
	global_store_dwordx4 v150, v[24:27], s[84:85] sc1
	s_add_u32 s84, s84, s62
	s_addc_u32 s85, s85, 0
	global_store_dwordx4 v150, v[28:31], s[84:85] sc1
	s_add_u32 s84, s84, s62
	s_addc_u32 s85, s85, 0
	global_store_dwordx4 v150, v[32:35], s[84:85] sc1
	s_add_u32 s84, s84, s62
	s_addc_u32 s85, s85, 0
	global_store_dwordx4 v150, v[36:39], s[84:85] sc1
	s_add_u32 s84, s84, s62
	s_addc_u32 s85, s85, 0
	global_store_dwordx4 v150, v[40:43], s[84:85] sc1
	s_add_u32 s84, s84, s62
	s_addc_u32 s85, s85, 0
	global_store_dwordx4 v150, v[44:47], s[84:85] sc1
	s_add_u32 s84, s84, s62
	s_addc_u32 s85, s85, 0
	global_store_dwordx4 v150, v[48:51], s[84:85] sc1
	s_add_u32 s84, s84, s62
	s_addc_u32 s85, s85, 0
	global_store_dwordx4 v150, v[52:55], s[84:85] sc1
	s_add_u32 s84, s84, s62
	s_addc_u32 s85, s85, 0
	global_store_dwordx4 v150, v[56:59], s[84:85] sc1
	s_add_u32 s84, s84, s62
	s_addc_u32 s85, s85, 0
	global_store_dwordx4 v150, v[60:63], s[84:85] sc1
	s_add_u32 s84, s84, s62
	s_addc_u32 s85, s85, 0
	global_store_dwordx4 v150, v[64:67], s[84:85] sc1
	s_add_u32 s84, s84, s62
	s_addc_u32 s85, s85, 0
	global_store_dwordx4 v150, v[68:71], s[84:85] sc1
	s_add_u32 s84, s84, s62
	s_addc_u32 s85, s85, 0
	global_store_dwordx4 v150, v[72:75], s[84:85] sc1
	s_add_u32 s84, s84, s62
	s_addc_u32 s85, s85, 0
	global_store_dwordx4 v150, v[76:79], s[84:85] sc1
	s_add_u32 s84, s84, s62
	s_addc_u32 s85, s85, 0
	global_store_dwordx4 v150, v[80:83], s[84:85] sc1
	s_add_u32 s84, s84, s62
	s_addc_u32 s85, s85, 0
	global_store_dwordx4 v150, v[84:87], s[84:85] sc1
	s_add_u32 s84, s84, s62
	s_addc_u32 s85, s85, 0
	global_store_dwordx4 v150, v[88:91], s[84:85] sc1
	s_add_u32 s84, s84, s62
	s_addc_u32 s85, s85, 0
	global_store_dwordx4 v150, v[92:95], s[84:85] sc1
	s_add_u32 s84, s84, s62
	s_addc_u32 s85, s85, 0
	global_store_dwordx4 v150, v[96:99], s[84:85] sc1
	s_add_u32 s84, s84, s62
	s_addc_u32 s85, s85, 0
	global_store_dwordx4 v150, v[100:103], s[84:85] sc1
	s_add_u32 s84, s84, s62
	s_addc_u32 s85, s85, 0
	global_store_dwordx4 v150, v[104:107], s[84:85] sc1
	s_add_u32 s84, s84, s62
	s_addc_u32 s85, s85, 0
	global_store_dwordx4 v150, v[108:111], s[84:85] sc1
	s_add_u32 s84, s84, s62
	s_addc_u32 s85, s85, 0
	global_store_dwordx4 v150, v[112:115], s[84:85] sc1
	s_add_u32 s84, s84, s62
	s_addc_u32 s85, s85, 0
	global_store_dwordx4 v150, v[116:119], s[84:85] sc1
	s_add_u32 s84, s84, s62
	s_addc_u32 s85, s85, 0
	global_store_dwordx4 v150, v[120:123], s[84:85] sc1
	s_add_u32 s84, s84, s62
	s_addc_u32 s85, s85, 0
	global_store_dwordx4 v150, v[124:127], s[84:85] sc1
	s_waitcnt vmcnt(0)
	s_barrier
	s_and_saveexec_b64 s[80:81], s[14:15]
	s_cbranch_execz .Lsk13_pdone
	v_mov_b32_e32 v151, 2
	v_mov_b32_e32 v152, s55
	v_add_u32_e32 v152, 0x3c00, v152
	global_store_dword v152, v151, s[24:25] sc1

.Lsk13_rload:
	s_mul_i32 s54, s99, 3
	s_lshl_b32 s55, s54, 2
	s_lshl_b32 s54, s54, 18
	s_add_u32 s84, s6, 0x4000000
	s_addc_u32 s85, s7, 0
	s_add_u32 s84, s84, s54
	s_addc_u32 s85, s85, 0
	s_movk_i32 s62, 0x2000
	v_lshlrev_b32_e32 v150, 4, v188
	s_and_saveexec_b64 s[80:81], s[14:15]
	s_cbranch_execz .Lsk13_polled
	v_mov_b32_e32 v152, s55
	v_add_u32_e32 v152, 0x3c00, v152
	s_mov_b32 s64, 0
.Lsk13_poll:
	global_load_dword v151, v152, s[24:25] sc1
	global_load_dword v153, v152, s[24:25] offset:4 sc1
	global_load_dword v154, v152, s[24:25] offset:8 sc1
	s_waitcnt vmcnt(0)
	v_and_b32_e32 v151, v151, v153
	v_and_b32_e32 v151, v151, v154
	s_nop 0
	v_readfirstlane_b32 s54, v151
	s_and_b32 s54, s54, 2
	s_cmp_lg_u32 s54, 0
	s_cbranch_scc1 .Lsk13_polled
	s_sleep 1
	s_add_i32 s64, s64, 1
	s_cmp_lt_u32 s64, 0x4000
	s_cbranch_scc1 .Lsk13_poll
